# barrier wait keeps four polls of the generation word in flight (was one load per round trip)
# speedup vs baseline: 1.0022x; 1.0022x over previous
; __device__ __forceinline__ unsigned xb_ld(unsigned* p)              { return __hip_atomic_load(p, __ATOMIC_RELAXED, __HIP_MEMORY_SCOPE_AGENT); }
; __device__ __forceinline__ unsigned xb_add(unsigned* p, unsigned v) { return __hip_atomic_fetch_add(p, v, __ATOMIC_RELAXED, __HIP_MEMORY_SCOPE_AGENT); }
; #define XB_SPIN(cond, bar) do { unsigned _sp = 0; while (cond) { __builtin_amdgcn_s_sleep(1); \
;     if ((++_sp & 255u) == 0u) { if (xb_ld(&(bar)[XB_TMO])) break; if (_sp > XB_SPIN_CAP) { atomicAdd(&(bar)[XB_TMO], 1u); break; } } } } while (0)
; __device__ __forceinline__ void xcd_barrier(const XcdBarrier& b) {
;     asm volatile("s_waitcnt vmcnt(0)" ::: "memory");
;     __syncthreads();
;     if (threadIdx.x == 0) {
;         unsigned* bar = b.bar;
;         __builtin_amdgcn_s_waitcnt(0);
;         unsigned nloc = b.st[0], nx = b.st[1];
;         if (nloc == 0u) { xcd_barrier_complete(bar, b.x, nloc, nx); b.st[0] = nloc; b.st[1] = nx; }
;         const unsigned old = xb_add(&bar[XB_XSUB(b.x)], 1u);
;         const unsigned gen = old / nloc;
;         if (old + 1u == (gen + 1u) * nloc) {
;             __builtin_amdgcn_fence(__ATOMIC_RELEASE, "agent");
;             asm volatile("s_waitcnt vmcnt(0)" ::: "memory");
;             const unsigned og = xb_add(&bar[XB_TOP], 1u);
;             const unsigned tg = og / nx;
;             if (og + 1u == (tg + 1u) * nx) xb_add(&bar[XB_TOPGEN], 1u);
;             else XB_SPIN(xb_ld(&bar[XB_TOPGEN]) == tg, bar);
;             __builtin_amdgcn_fence(__ATOMIC_ACQUIRE, "agent");
;             xb_add(&bar[XB_XGEN(b.x)], 1u);
;             asm volatile("s_waitcnt vmcnt(0)" ::: "memory");
;         } else {
;             XB_SPIN(xb_ld(&bar[XB_XGEN(b.x)]) == gen, bar);
;             __builtin_amdgcn_fence(__ATOMIC_ACQUIRE, "agent");
;             asm volatile("s_waitcnt vmcnt(0)" ::: "memory");
;         }
.LBB0_129:
	v_readlane_b32 s4, v236, 18
	s_lshl_b32 s4, s4, 8
	s_add_u32 s4, s28, s4
	s_addc_u32 s5, s29, 0
	v_mov_b32_e32 v1, 0x1000
	v_mov_b32_e32 v3, 1
	global_atomic_add v3, v1, v3, s[4:5] offset:1024 sc0
	v_cvt_f32_u32_e32 v1, v2
	v_sub_u32_e32 v4, 0, v2
	v_rcp_iflag_f32_e32 v1, v1
	s_nop 0
	v_mul_f32_e32 v1, 0x4f7ffffe, v1
	v_cvt_u32_f32_e32 v1, v1
	v_mul_lo_u32 v4, v4, v1
	v_mul_hi_u32 v4, v1, v4
	v_add_u32_e32 v1, v1, v4
	s_waitcnt vmcnt(0)
	v_mul_hi_u32 v1, v3, v1
	v_mul_lo_u32 v4, v1, v2
	v_sub_u32_e32 v4, v3, v4
	v_add_u32_e32 v5, 1, v1
	v_cmp_ge_u32_e32 vcc, v4, v2
	v_add_u32_e32 v3, 1, v3
	s_nop 0
	v_cndmask_b32_e32 v1, v1, v5, vcc
	v_sub_u32_e32 v5, v4, v2
	v_cndmask_b32_e32 v4, v4, v5, vcc
	v_add_u32_e32 v5, 1, v1
	v_cmp_ge_u32_e32 vcc, v4, v2
	s_nop 1
	v_cndmask_b32_e32 v1, v1, v5, vcc
	v_mul_lo_u32 v4, v2, v1
	v_add_u32_e32 v2, v4, v2
	v_cmp_ne_u32_e32 vcc, v3, v2
	s_and_saveexec_b64 s[6:7], vcc
	s_xor_b64 s[6:7], exec, s[6:7]
	s_cbranch_execz .LBB0_143
	s_waitcnt lgkmcnt(0)
	v_mov_b32_e32 v0, 0x3000
	global_load_dword v0, v0, s[28:29] offset:1280 sc1
	s_add_u32 s10, s28, 0x3500
	s_addc_u32 s11, s29, 0
	s_waitcnt vmcnt(0)
	v_cmp_eq_u32_e32 vcc, v0, v1
	s_and_saveexec_b64 s[8:9], vcc
	s_cbranch_execz .LBB0_142
	v_mov_b32_e32 v0, 0
	s_mov_b64 s[12:13], exec
	s_mov_b64 s[14:15], -1
	s_mov_b32 s22, 0
	global_load_dword v2, v0, s[10:11] sc1
	s_sleep 3
	global_load_dword v3, v0, s[10:11] sc1
	s_sleep 3
	global_load_dword v4, v0, s[10:11] sc1
	s_sleep 3
	global_load_dword v5, v0, s[10:11] sc1
.Lpoll_loop_0:
	s_waitcnt vmcnt(3)
	v_cmp_ne_u32_e32 vcc, v2, v1
	s_cbranch_vccnz .Lpoll_done_0
	global_load_dword v2, v0, s[10:11] sc1
	s_sleep 3
	s_waitcnt vmcnt(3)
	v_cmp_ne_u32_e32 vcc, v3, v1
	s_cbranch_vccnz .Lpoll_done_0
	global_load_dword v3, v0, s[10:11] sc1
	s_sleep 3
	s_waitcnt vmcnt(3)
	v_cmp_ne_u32_e32 vcc, v4, v1
	s_cbranch_vccnz .Lpoll_done_0
	global_load_dword v4, v0, s[10:11] sc1
	s_sleep 3
	s_waitcnt vmcnt(3)
	v_cmp_ne_u32_e32 vcc, v5, v1
	s_cbranch_vccnz .Lpoll_done_0
	global_load_dword v5, v0, s[10:11] sc1
	s_sleep 3
	s_add_i32 s22, s22, 1
	s_cmp_lt_u32 s22, 0x100000
	s_cbranch_scc1 .Lpoll_loop_0
	s_mov_b64 s[14:15], 0
.Lpoll_done_0:
	s_waitcnt vmcnt(0)
.LBB0_139:
	s_or_b64 exec, exec, s[12:13]
	s_xor_b64 s[10:11], s[14:15], -1
	s_and_saveexec_b64 s[12:13], s[10:11]
	s_xor_b64 s[12:13], exec, s[12:13]
	s_cbranch_execz .LBB0_142
	s_mov_b64 s[10:11], exec
	v_mbcnt_lo_u32_b32 v0, s10, 0
	v_mbcnt_hi_u32_b32 v0, s11, v0
	v_cmp_eq_u32_e32 vcc, 0, v0
	s_and_b64 s[12:13], exec, vcc
	s_mov_b64 exec, s[12:13]
	s_cbranch_execz .LBB0_142
	s_bcnt1_i32_b64 s10, s[10:11]
	v_mov_b32_e32 v0, 0
	v_mov_b32_e32 v1, s10
	global_atomic_add v0, v1, s[28:29] offset:512

; __device__ __forceinline__ unsigned xb_ld(unsigned* p)              { return __hip_atomic_load(p, __ATOMIC_RELAXED, __HIP_MEMORY_SCOPE_AGENT); }
; __device__ __forceinline__ unsigned xb_add(unsigned* p, unsigned v) { return __hip_atomic_fetch_add(p, v, __ATOMIC_RELAXED, __HIP_MEMORY_SCOPE_AGENT); }
; #define XB_SPIN(cond, bar) do { unsigned _sp = 0; while (cond) { __builtin_amdgcn_s_sleep(1); \
;     if ((++_sp & 255u) == 0u) { if (xb_ld(&(bar)[XB_TMO])) break; if (_sp > XB_SPIN_CAP) { atomicAdd(&(bar)[XB_TMO], 1u); break; } } } } while (0)
; __device__ __forceinline__ void xcd_barrier(const XcdBarrier& b) {
;     ...
;             else XB_SPIN(xb_ld(&bar[XB_TOPGEN]) == tg, bar);
;             __builtin_amdgcn_fence(__ATOMIC_ACQUIRE, "agent");
;             xb_add(&bar[XB_XGEN(b.x)], 1u);
;             asm volatile("s_waitcnt vmcnt(0)" ::: "memory");
;         } else {
;             XB_SPIN(xb_ld(&bar[XB_XGEN(b.x)]) == gen, bar);
.Lpoll_done_1:
	s_waitcnt vmcnt(0)
.LBB0_254:
	s_or_b64 exec, exec, s[12:13]
	s_xor_b64 s[10:11], s[14:15], -1
	s_and_saveexec_b64 s[12:13], s[10:11]
	s_xor_b64 s[12:13], exec, s[12:13]
	s_cbranch_execz .LBB0_257
	s_mov_b64 s[10:11], exec
	v_mbcnt_lo_u32_b32 v0, s10, 0
	v_mbcnt_hi_u32_b32 v0, s11, v0
	v_cmp_eq_u32_e32 vcc, 0, v0
	s_and_b64 s[12:13], exec, vcc
	s_mov_b64 exec, s[12:13]
	s_cbranch_execz .LBB0_257
	s_bcnt1_i32_b64 s10, s[10:11]
	v_mov_b32_e32 v0, 0
	v_mov_b32_e32 v1, s10
	global_atomic_add v0, v1, s[28:29] offset:512

; __device__ __forceinline__ unsigned xb_ld(unsigned* p)              { return __hip_atomic_load(p, __ATOMIC_RELAXED, __HIP_MEMORY_SCOPE_AGENT); }
; __device__ __forceinline__ unsigned xb_add(unsigned* p, unsigned v) { return __hip_atomic_fetch_add(p, v, __ATOMIC_RELAXED, __HIP_MEMORY_SCOPE_AGENT); }
; #define XB_SPIN(cond, bar) do { unsigned _sp = 0; while (cond) { __builtin_amdgcn_s_sleep(1); \
;     if ((++_sp & 255u) == 0u) { if (xb_ld(&(bar)[XB_TMO])) break; if (_sp > XB_SPIN_CAP) { atomicAdd(&(bar)[XB_TMO], 1u); break; } } } } while (0)
; __device__ __forceinline__ void xcd_barrier(const XcdBarrier& b) {
;     ...
;             else XB_SPIN(xb_ld(&bar[XB_TOPGEN]) == tg, bar);
;             __builtin_amdgcn_fence(__ATOMIC_ACQUIRE, "agent");
;             xb_add(&bar[XB_XGEN(b.x)], 1u);
;             asm volatile("s_waitcnt vmcnt(0)" ::: "memory");
;         } else {
;             XB_SPIN(xb_ld(&bar[XB_XGEN(b.x)]) == gen, bar);
.Lpoll_done_2:
	s_waitcnt vmcnt(0)
.LBB0_347:
	s_or_b64 exec, exec, s[12:13]
	s_xor_b64 s[10:11], s[14:15], -1
	s_and_saveexec_b64 s[12:13], s[10:11]
	s_xor_b64 s[12:13], exec, s[12:13]
	s_cbranch_execz .LBB0_350
	s_mov_b64 s[10:11], exec
	v_mbcnt_lo_u32_b32 v0, s10, 0
	v_mbcnt_hi_u32_b32 v0, s11, v0
	v_cmp_eq_u32_e32 vcc, 0, v0
	s_and_b64 s[12:13], exec, vcc
	s_mov_b64 exec, s[12:13]
	s_cbranch_execz .LBB0_350
	s_bcnt1_i32_b64 s10, s[10:11]
	v_mov_b32_e32 v0, 0
	v_mov_b32_e32 v1, s10
	global_atomic_add v0, v1, s[28:29] offset:512

; __device__ __forceinline__ unsigned xb_ld(unsigned* p)              { return __hip_atomic_load(p, __ATOMIC_RELAXED, __HIP_MEMORY_SCOPE_AGENT); }
; __device__ __forceinline__ unsigned xb_add(unsigned* p, unsigned v) { return __hip_atomic_fetch_add(p, v, __ATOMIC_RELAXED, __HIP_MEMORY_SCOPE_AGENT); }
; #define XB_SPIN(cond, bar) do { unsigned _sp = 0; while (cond) { __builtin_amdgcn_s_sleep(1); \
;     if ((++_sp & 255u) == 0u) { if (xb_ld(&(bar)[XB_TMO])) break; if (_sp > XB_SPIN_CAP) { atomicAdd(&(bar)[XB_TMO], 1u); break; } } } } while (0)
; __device__ __forceinline__ void xcd_barrier(const XcdBarrier& b) {
;     ...
;             else XB_SPIN(xb_ld(&bar[XB_TOPGEN]) == tg, bar);
;             __builtin_amdgcn_fence(__ATOMIC_ACQUIRE, "agent");
;             xb_add(&bar[XB_XGEN(b.x)], 1u);
;             asm volatile("s_waitcnt vmcnt(0)" ::: "memory");
;         } else {
;             XB_SPIN(xb_ld(&bar[XB_XGEN(b.x)]) == gen, bar);
.Lpoll_done_3:
	s_waitcnt vmcnt(0)
.LBB0_426:
	s_or_b64 exec, exec, s[12:13]
	s_xor_b64 s[10:11], s[14:15], -1
	s_and_saveexec_b64 s[12:13], s[10:11]
	s_xor_b64 s[12:13], exec, s[12:13]
	s_cbranch_execz .LBB0_429
	s_mov_b64 s[10:11], exec
	v_mbcnt_lo_u32_b32 v0, s10, 0
	v_mbcnt_hi_u32_b32 v0, s11, v0
	v_cmp_eq_u32_e32 vcc, 0, v0
	s_and_b64 s[12:13], exec, vcc
	s_mov_b64 exec, s[12:13]
	s_cbranch_execz .LBB0_429
	s_bcnt1_i32_b64 s10, s[10:11]
	v_mov_b32_e32 v0, 0
	v_mov_b32_e32 v1, s10
	global_atomic_add v0, v1, s[28:29] offset:512

; __device__ __forceinline__ unsigned xb_ld(unsigned* p)              { return __hip_atomic_load(p, __ATOMIC_RELAXED, __HIP_MEMORY_SCOPE_AGENT); }
; __device__ __forceinline__ unsigned xb_add(unsigned* p, unsigned v) { return __hip_atomic_fetch_add(p, v, __ATOMIC_RELAXED, __HIP_MEMORY_SCOPE_AGENT); }
; #define XB_SPIN(cond, bar) do { unsigned _sp = 0; while (cond) { __builtin_amdgcn_s_sleep(1); \
;     if ((++_sp & 255u) == 0u) { if (xb_ld(&(bar)[XB_TMO])) break; if (_sp > XB_SPIN_CAP) { atomicAdd(&(bar)[XB_TMO], 1u); break; } } } } while (0)
; __device__ __forceinline__ void xcd_barrier(const XcdBarrier& b) {
;     ...
;             else XB_SPIN(xb_ld(&bar[XB_TOPGEN]) == tg, bar);
;             __builtin_amdgcn_fence(__ATOMIC_ACQUIRE, "agent");
;             xb_add(&bar[XB_XGEN(b.x)], 1u);
;             asm volatile("s_waitcnt vmcnt(0)" ::: "memory");
;         } else {
;             XB_SPIN(xb_ld(&bar[XB_XGEN(b.x)]) == gen, bar);
.Lpoll_done_4:
	s_waitcnt vmcnt(0)
.LBB0_479:
	s_or_b64 exec, exec, s[12:13]
	s_xor_b64 s[10:11], s[14:15], -1
	s_and_saveexec_b64 s[12:13], s[10:11]
	s_xor_b64 s[12:13], exec, s[12:13]
	s_cbranch_execz .LBB0_482
	s_mov_b64 s[10:11], exec
	v_mbcnt_lo_u32_b32 v0, s10, 0
	v_mbcnt_hi_u32_b32 v0, s11, v0
	v_cmp_eq_u32_e32 vcc, 0, v0
	s_and_b64 s[12:13], exec, vcc
	s_mov_b64 exec, s[12:13]
	s_cbranch_execz .LBB0_482
	s_bcnt1_i32_b64 s10, s[10:11]
	v_mov_b32_e32 v0, 0
	v_mov_b32_e32 v1, s10
	global_atomic_add v0, v1, s[28:29] offset:512

; __device__ __forceinline__ unsigned xb_ld(unsigned* p)              { return __hip_atomic_load(p, __ATOMIC_RELAXED, __HIP_MEMORY_SCOPE_AGENT); }
; __device__ __forceinline__ unsigned xb_add(unsigned* p, unsigned v) { return __hip_atomic_fetch_add(p, v, __ATOMIC_RELAXED, __HIP_MEMORY_SCOPE_AGENT); }
; #define XB_SPIN(cond, bar) do { unsigned _sp = 0; while (cond) { __builtin_amdgcn_s_sleep(1); \
;     if ((++_sp & 255u) == 0u) { if (xb_ld(&(bar)[XB_TMO])) break; if (_sp > XB_SPIN_CAP) { atomicAdd(&(bar)[XB_TMO], 1u); break; } } } } while (0)
; __device__ __forceinline__ void xcd_barrier(const XcdBarrier& b) {
;     ...
;             else XB_SPIN(xb_ld(&bar[XB_TOPGEN]) == tg, bar);
;             __builtin_amdgcn_fence(__ATOMIC_ACQUIRE, "agent");
;             xb_add(&bar[XB_XGEN(b.x)], 1u);
;             asm volatile("s_waitcnt vmcnt(0)" ::: "memory");
;         } else {
;             XB_SPIN(xb_ld(&bar[XB_XGEN(b.x)]) == gen, bar);
.Lpoll_done_5:
	s_waitcnt vmcnt(0)
.LBB0_550:
	s_or_b64 exec, exec, s[12:13]
	s_xor_b64 s[10:11], s[14:15], -1
	s_and_saveexec_b64 s[12:13], s[10:11]
	s_xor_b64 s[12:13], exec, s[12:13]
	s_cbranch_execz .LBB0_553
	s_mov_b64 s[10:11], exec
	v_mbcnt_lo_u32_b32 v0, s10, 0
	v_mbcnt_hi_u32_b32 v0, s11, v0
	v_cmp_eq_u32_e32 vcc, 0, v0
	s_and_b64 s[12:13], exec, vcc
	s_mov_b64 exec, s[12:13]
	s_cbranch_execz .LBB0_553
	s_bcnt1_i32_b64 s10, s[10:11]
	v_mov_b32_e32 v0, 0
	v_mov_b32_e32 v1, s10
	global_atomic_add v0, v1, s[28:29] offset:512

; __device__ __forceinline__ unsigned xb_ld(unsigned* p)              { return __hip_atomic_load(p, __ATOMIC_RELAXED, __HIP_MEMORY_SCOPE_AGENT); }
; __device__ __forceinline__ unsigned xb_add(unsigned* p, unsigned v) { return __hip_atomic_fetch_add(p, v, __ATOMIC_RELAXED, __HIP_MEMORY_SCOPE_AGENT); }
; #define XB_SPIN(cond, bar) do { unsigned _sp = 0; while (cond) { __builtin_amdgcn_s_sleep(1); \
;     if ((++_sp & 255u) == 0u) { if (xb_ld(&(bar)[XB_TMO])) break; if (_sp > XB_SPIN_CAP) { atomicAdd(&(bar)[XB_TMO], 1u); break; } } } } while (0)
; __device__ __forceinline__ void xcd_barrier(const XcdBarrier& b) {
;     ...
;             else XB_SPIN(xb_ld(&bar[XB_TOPGEN]) == tg, bar);
;             __builtin_amdgcn_fence(__ATOMIC_ACQUIRE, "agent");
;             xb_add(&bar[XB_XGEN(b.x)], 1u);
;             asm volatile("s_waitcnt vmcnt(0)" ::: "memory");
;         } else {
;             XB_SPIN(xb_ld(&bar[XB_XGEN(b.x)]) == gen, bar);
.Lpoll_done_6:
	s_waitcnt vmcnt(0)
.LBB0_629:
	s_or_b64 exec, exec, s[12:13]
	s_xor_b64 s[10:11], s[14:15], -1
	s_and_saveexec_b64 s[12:13], s[10:11]
	s_xor_b64 s[12:13], exec, s[12:13]
	s_cbranch_execz .LBB0_632
	s_mov_b64 s[10:11], exec
	v_mbcnt_lo_u32_b32 v0, s10, 0
	v_mbcnt_hi_u32_b32 v0, s11, v0
	v_cmp_eq_u32_e32 vcc, 0, v0
	s_and_b64 s[12:13], exec, vcc
	s_mov_b64 exec, s[12:13]
	s_cbranch_execz .LBB0_632
	s_bcnt1_i32_b64 s10, s[10:11]
	v_mov_b32_e32 v0, 0
	v_mov_b32_e32 v1, s10
	global_atomic_add v0, v1, s[28:29] offset:512

; __device__ __forceinline__ unsigned xb_ld(unsigned* p)              { return __hip_atomic_load(p, __ATOMIC_RELAXED, __HIP_MEMORY_SCOPE_AGENT); }
; __device__ __forceinline__ unsigned xb_add(unsigned* p, unsigned v) { return __hip_atomic_fetch_add(p, v, __ATOMIC_RELAXED, __HIP_MEMORY_SCOPE_AGENT); }
; #define XB_SPIN(cond, bar) do { unsigned _sp = 0; while (cond) { __builtin_amdgcn_s_sleep(1); \
;     if ((++_sp & 255u) == 0u) { if (xb_ld(&(bar)[XB_TMO])) break; if (_sp > XB_SPIN_CAP) { atomicAdd(&(bar)[XB_TMO], 1u); break; } } } } while (0)
; __device__ __forceinline__ void xcd_barrier(const XcdBarrier& b) {
;     ...
;             else XB_SPIN(xb_ld(&bar[XB_TOPGEN]) == tg, bar);
;             __builtin_amdgcn_fence(__ATOMIC_ACQUIRE, "agent");
;             xb_add(&bar[XB_XGEN(b.x)], 1u);
;             asm volatile("s_waitcnt vmcnt(0)" ::: "memory");
;         } else {
;             XB_SPIN(xb_ld(&bar[XB_XGEN(b.x)]) == gen, bar);
.Lpoll_done_7:
	s_waitcnt vmcnt(0)
.LBB0_722:
	s_or_b64 exec, exec, s[12:13]
	s_xor_b64 s[10:11], s[14:15], -1
	s_and_saveexec_b64 s[12:13], s[10:11]
	s_xor_b64 s[12:13], exec, s[12:13]
	s_cbranch_execz .LBB0_725
	s_mov_b64 s[10:11], exec
	v_mbcnt_lo_u32_b32 v0, s10, 0
	v_mbcnt_hi_u32_b32 v0, s11, v0
	v_cmp_eq_u32_e32 vcc, 0, v0
	s_and_b64 s[12:13], exec, vcc
	s_mov_b64 exec, s[12:13]
	s_cbranch_execz .LBB0_725
	s_bcnt1_i32_b64 s10, s[10:11]
	v_mov_b32_e32 v0, 0
	v_mov_b32_e32 v1, s10
	global_atomic_add v0, v1, s[28:29] offset:512

; __device__ __forceinline__ unsigned xb_ld(unsigned* p)              { return __hip_atomic_load(p, __ATOMIC_RELAXED, __HIP_MEMORY_SCOPE_AGENT); }
; __device__ __forceinline__ unsigned xb_add(unsigned* p, unsigned v) { return __hip_atomic_fetch_add(p, v, __ATOMIC_RELAXED, __HIP_MEMORY_SCOPE_AGENT); }
; #define XB_SPIN(cond, bar) do { unsigned _sp = 0; while (cond) { __builtin_amdgcn_s_sleep(1); \
;     if ((++_sp & 255u) == 0u) { if (xb_ld(&(bar)[XB_TMO])) break; if (_sp > XB_SPIN_CAP) { atomicAdd(&(bar)[XB_TMO], 1u); break; } } } } while (0)
; __device__ __forceinline__ void xcd_barrier(const XcdBarrier& b) {
;     ...
;             else XB_SPIN(xb_ld(&bar[XB_TOPGEN]) == tg, bar);
;             __builtin_amdgcn_fence(__ATOMIC_ACQUIRE, "agent");
;             xb_add(&bar[XB_XGEN(b.x)], 1u);
;             asm volatile("s_waitcnt vmcnt(0)" ::: "memory");
;         } else {
;             XB_SPIN(xb_ld(&bar[XB_XGEN(b.x)]) == gen, bar);
.Lpoll_done_8:
	s_waitcnt vmcnt(0)
.LBB0_832:
	s_or_b64 exec, exec, s[12:13]
	s_xor_b64 s[10:11], s[14:15], -1
	s_and_saveexec_b64 s[12:13], s[10:11]
	s_xor_b64 s[12:13], exec, s[12:13]
	s_cbranch_execz .LBB0_835
	s_mov_b64 s[10:11], exec
	v_mbcnt_lo_u32_b32 v0, s10, 0
	v_mbcnt_hi_u32_b32 v0, s11, v0
	v_cmp_eq_u32_e32 vcc, 0, v0
	s_and_b64 s[12:13], exec, vcc
	s_mov_b64 exec, s[12:13]
	s_cbranch_execz .LBB0_835
	s_bcnt1_i32_b64 s10, s[10:11]
	v_mov_b32_e32 v0, 0
	v_mov_b32_e32 v1, s10
	global_atomic_add v0, v1, s[28:29] offset:512

; __device__ __forceinline__ unsigned xb_ld(unsigned* p)              { return __hip_atomic_load(p, __ATOMIC_RELAXED, __HIP_MEMORY_SCOPE_AGENT); }
; __device__ __forceinline__ unsigned xb_add(unsigned* p, unsigned v) { return __hip_atomic_fetch_add(p, v, __ATOMIC_RELAXED, __HIP_MEMORY_SCOPE_AGENT); }
; #define XB_SPIN(cond, bar) do { unsigned _sp = 0; while (cond) { __builtin_amdgcn_s_sleep(1); \
;     if ((++_sp & 255u) == 0u) { if (xb_ld(&(bar)[XB_TMO])) break; if (_sp > XB_SPIN_CAP) { atomicAdd(&(bar)[XB_TMO], 1u); break; } } } } while (0)
; __device__ __forceinline__ void xcd_barrier(const XcdBarrier& b) {
;     ...
;             else XB_SPIN(xb_ld(&bar[XB_TOPGEN]) == tg, bar);
;             __builtin_amdgcn_fence(__ATOMIC_ACQUIRE, "agent");
;             xb_add(&bar[XB_XGEN(b.x)], 1u);
;             asm volatile("s_waitcnt vmcnt(0)" ::: "memory");
;         } else {
;             XB_SPIN(xb_ld(&bar[XB_XGEN(b.x)]) == gen, bar);
.Lpoll_done_9:
	s_waitcnt vmcnt(0)
.LBB0_987:
	s_or_b64 exec, exec, s[12:13]
	s_xor_b64 s[10:11], s[14:15], -1
	s_and_saveexec_b64 s[12:13], s[10:11]
	s_xor_b64 s[12:13], exec, s[12:13]
	s_cbranch_execz .LBB0_990
	s_mov_b64 s[10:11], exec
	v_mbcnt_lo_u32_b32 v0, s10, 0
	v_mbcnt_hi_u32_b32 v0, s11, v0
	v_cmp_eq_u32_e32 vcc, 0, v0
	s_and_b64 s[12:13], exec, vcc
	s_mov_b64 exec, s[12:13]
	s_cbranch_execz .LBB0_990
	s_bcnt1_i32_b64 s10, s[10:11]
	v_mov_b32_e32 v0, 0
	v_mov_b32_e32 v1, s10
	global_atomic_add v0, v1, s[28:29] offset:512

; __device__ __forceinline__ unsigned xb_ld(unsigned* p)              { return __hip_atomic_load(p, __ATOMIC_RELAXED, __HIP_MEMORY_SCOPE_AGENT); }
; __device__ __forceinline__ unsigned xb_add(unsigned* p, unsigned v) { return __hip_atomic_fetch_add(p, v, __ATOMIC_RELAXED, __HIP_MEMORY_SCOPE_AGENT); }
; #define XB_SPIN(cond, bar) do { unsigned _sp = 0; while (cond) { __builtin_amdgcn_s_sleep(1); \
;     if ((++_sp & 255u) == 0u) { if (xb_ld(&(bar)[XB_TMO])) break; if (_sp > XB_SPIN_CAP) { atomicAdd(&(bar)[XB_TMO], 1u); break; } } } } while (0)
; __device__ __forceinline__ void xcd_barrier(const XcdBarrier& b) {
;     ...
;             else XB_SPIN(xb_ld(&bar[XB_TOPGEN]) == tg, bar);
;             __builtin_amdgcn_fence(__ATOMIC_ACQUIRE, "agent");
;             xb_add(&bar[XB_XGEN(b.x)], 1u);
;             asm volatile("s_waitcnt vmcnt(0)" ::: "memory");
;         } else {
;             XB_SPIN(xb_ld(&bar[XB_XGEN(b.x)]) == gen, bar);
.Lpoll_done_10:
	s_waitcnt vmcnt(0)
.LBB0_1066:
	s_or_b64 exec, exec, s[12:13]
	s_xor_b64 s[10:11], s[14:15], -1
	s_and_saveexec_b64 s[12:13], s[10:11]
	s_xor_b64 s[12:13], exec, s[12:13]
	s_cbranch_execz .LBB0_1069
	s_mov_b64 s[10:11], exec
	v_mbcnt_lo_u32_b32 v0, s10, 0
	v_mbcnt_hi_u32_b32 v0, s11, v0
	v_cmp_eq_u32_e32 vcc, 0, v0
	s_and_b64 s[12:13], exec, vcc
	s_mov_b64 exec, s[12:13]
	s_cbranch_execz .LBB0_1069
	s_bcnt1_i32_b64 s10, s[10:11]
	v_mov_b32_e32 v0, 0
	v_mov_b32_e32 v1, s10
	global_atomic_add v0, v1, s[28:29] offset:512

; __device__ __forceinline__ unsigned xb_ld(unsigned* p)              { return __hip_atomic_load(p, __ATOMIC_RELAXED, __HIP_MEMORY_SCOPE_AGENT); }
; __device__ __forceinline__ unsigned xb_add(unsigned* p, unsigned v) { return __hip_atomic_fetch_add(p, v, __ATOMIC_RELAXED, __HIP_MEMORY_SCOPE_AGENT); }
; #define XB_SPIN(cond, bar) do { unsigned _sp = 0; while (cond) { __builtin_amdgcn_s_sleep(1); \
;     if ((++_sp & 255u) == 0u) { if (xb_ld(&(bar)[XB_TMO])) break; if (_sp > XB_SPIN_CAP) { atomicAdd(&(bar)[XB_TMO], 1u); break; } } } } while (0)
; __device__ __forceinline__ void xcd_barrier(const XcdBarrier& b) {
;     ...
;             else XB_SPIN(xb_ld(&bar[XB_TOPGEN]) == tg, bar);
;             __builtin_amdgcn_fence(__ATOMIC_ACQUIRE, "agent");
;             xb_add(&bar[XB_XGEN(b.x)], 1u);
;             asm volatile("s_waitcnt vmcnt(0)" ::: "memory");
;         } else {
;             XB_SPIN(xb_ld(&bar[XB_XGEN(b.x)]) == gen, bar);
.Lpoll_done_11:
	s_waitcnt vmcnt(0)
.LBB0_1119:
	s_or_b64 exec, exec, s[12:13]
	s_xor_b64 s[10:11], s[14:15], -1
	s_and_saveexec_b64 s[12:13], s[10:11]
	s_xor_b64 s[12:13], exec, s[12:13]
	s_cbranch_execz .LBB0_1122
	s_mov_b64 s[10:11], exec
	v_mbcnt_lo_u32_b32 v0, s10, 0
	v_mbcnt_hi_u32_b32 v0, s11, v0
	v_cmp_eq_u32_e32 vcc, 0, v0
	s_and_b64 s[12:13], exec, vcc
	s_mov_b64 exec, s[12:13]
	s_cbranch_execz .LBB0_1122
	s_bcnt1_i32_b64 s10, s[10:11]
	v_mov_b32_e32 v0, 0
	v_mov_b32_e32 v1, s10
	global_atomic_add v0, v1, s[28:29] offset:512

; __device__ __forceinline__ unsigned xb_ld(unsigned* p)              { return __hip_atomic_load(p, __ATOMIC_RELAXED, __HIP_MEMORY_SCOPE_AGENT); }
; __device__ __forceinline__ unsigned xb_add(unsigned* p, unsigned v) { return __hip_atomic_fetch_add(p, v, __ATOMIC_RELAXED, __HIP_MEMORY_SCOPE_AGENT); }
; #define XB_SPIN(cond, bar) do { unsigned _sp = 0; while (cond) { __builtin_amdgcn_s_sleep(1); \
;     if ((++_sp & 255u) == 0u) { if (xb_ld(&(bar)[XB_TMO])) break; if (_sp > XB_SPIN_CAP) { atomicAdd(&(bar)[XB_TMO], 1u); break; } } } } while (0)
; __device__ __forceinline__ void xcd_barrier(const XcdBarrier& b) {
;     ...
;             else XB_SPIN(xb_ld(&bar[XB_TOPGEN]) == tg, bar);
;             __builtin_amdgcn_fence(__ATOMIC_ACQUIRE, "agent");
;             xb_add(&bar[XB_XGEN(b.x)], 1u);
;             asm volatile("s_waitcnt vmcnt(0)" ::: "memory");
;         } else {
;             XB_SPIN(xb_ld(&bar[XB_XGEN(b.x)]) == gen, bar);
.Lpoll_done_12:
	s_waitcnt vmcnt(0)
.LBB0_1190:
	s_or_b64 exec, exec, s[12:13]
	s_xor_b64 s[10:11], s[14:15], -1
	s_and_saveexec_b64 s[12:13], s[10:11]
	s_xor_b64 s[12:13], exec, s[12:13]
	s_cbranch_execz .LBB0_1193
	s_mov_b64 s[10:11], exec
	v_mbcnt_lo_u32_b32 v0, s10, 0
	v_mbcnt_hi_u32_b32 v0, s11, v0
	v_cmp_eq_u32_e32 vcc, 0, v0
	s_and_b64 s[12:13], exec, vcc
	s_mov_b64 exec, s[12:13]
	s_cbranch_execz .LBB0_1193
	s_bcnt1_i32_b64 s10, s[10:11]
	v_mov_b32_e32 v0, 0
	v_mov_b32_e32 v1, s10
	global_atomic_add v0, v1, s[28:29] offset:512

; __device__ __forceinline__ unsigned xb_ld(unsigned* p)              { return __hip_atomic_load(p, __ATOMIC_RELAXED, __HIP_MEMORY_SCOPE_AGENT); }
; __device__ __forceinline__ unsigned xb_add(unsigned* p, unsigned v) { return __hip_atomic_fetch_add(p, v, __ATOMIC_RELAXED, __HIP_MEMORY_SCOPE_AGENT); }
; #define XB_SPIN(cond, bar) do { unsigned _sp = 0; while (cond) { __builtin_amdgcn_s_sleep(1); \
;     if ((++_sp & 255u) == 0u) { if (xb_ld(&(bar)[XB_TMO])) break; if (_sp > XB_SPIN_CAP) { atomicAdd(&(bar)[XB_TMO], 1u); break; } } } } while (0)
; __device__ __forceinline__ void xcd_barrier(const XcdBarrier& b) {
;     ...
;             else XB_SPIN(xb_ld(&bar[XB_TOPGEN]) == tg, bar);
;             __builtin_amdgcn_fence(__ATOMIC_ACQUIRE, "agent");
;             xb_add(&bar[XB_XGEN(b.x)], 1u);
;             asm volatile("s_waitcnt vmcnt(0)" ::: "memory");
;         } else {
;             XB_SPIN(xb_ld(&bar[XB_XGEN(b.x)]) == gen, bar);
.Lpoll_done_13:
	s_waitcnt vmcnt(0)
.LBB0_1269:
	s_or_b64 exec, exec, s[12:13]
	s_xor_b64 s[10:11], s[14:15], -1
	s_and_saveexec_b64 s[12:13], s[10:11]
	s_xor_b64 s[12:13], exec, s[12:13]
	s_cbranch_execz .LBB0_1272
	s_mov_b64 s[10:11], exec
	v_mbcnt_lo_u32_b32 v0, s10, 0
	v_mbcnt_hi_u32_b32 v0, s11, v0
	v_cmp_eq_u32_e32 vcc, 0, v0
	s_and_b64 s[12:13], exec, vcc
	s_mov_b64 exec, s[12:13]
	s_cbranch_execz .LBB0_1272
	s_bcnt1_i32_b64 s10, s[10:11]
	v_mov_b32_e32 v0, 0
	v_mov_b32_e32 v1, s10
	global_atomic_add v0, v1, s[28:29] offset:512
